# SGPR-base DMA addressing extended to w_out and ffn_down K-loops
# speedup vs baseline: 1.0483x; 1.0045x over previous
; DI int tid_() { int t = threadIdx.x; asm volatile("" : "+v"(t)); return t; }
;     ...
;   const int tid = tid_(), w = tid >> 6, l = tid & 63, r16 = l & 15, q4 = l >> 4;
;   const int wm = w >> 2, wn = w & 3;
;   f32x4 acc[MT][4];
; #pragma unroll
;   for (int a = 0; a < MT; ++a)
; #pragma unroll
;     for (int b = 0; b < 4; ++b) { acc[a][b][0] = 0.f; acc[a][b][1] = 0.f; acc[a][b][2] = 0.f; acc[a][b][3] = 0.f; }
;   const int srow = tid >> 3, slog = (tid & 7) ^ ((tid >> 4) & 7);
;   const bf16_t* Ag = A + (size_t)(m0 + srow) * lda + slog * 8;
;   const bf16_t* Bg0 = B + (size_t)min(n0 + srow, N - 1) * ldb + slog * 8;
;   const bf16_t* Bg1 = B + (size_t)min(n0 + srow + 64, N - 1) * ldb + slog * 8;
;   const bf16_t* Bg2 = B + (size_t)min(n0 + srow + 128, N - 1) * ldb + slog * 8;
;   const bf16_t* Bg3 = B + (size_t)min(n0 + srow + 192, N - 1) * ldb + slog * 8;
;   char* wbase = smem + w * 1024;
;     ...
;   const int nk = K >> 6;
;   __syncthreads();
;   STAGE_TILE(0, 0)
;   asm volatile("s_waitcnt vmcnt(0)" ::: "memory");
;   __syncthreads();
.LBB0_47:
	v_mov_b32_e32 v16, v0
	v_readlane_b32 s52, v253, 40
	v_lshrrev_b32_e32 v17, 4, v16
	s_lshl_b32 s40, s40, 8
	v_ashrrev_i32_e32 v4, 3, v16
	v_xor_b32_e32 v5, v17, v16
	v_readlane_b32 s54, v253, 42
	v_readlane_b32 s55, v253, 43
	s_lshl_b32 s39, s41, 8
	v_add_u32_e32 v6, s40, v4
	v_mov_b64_e32 v[2:3], s[54:55]
	s_movk_i32 s41, 0x1600
	v_lshlrev_b32_e32 v5, 4, v5
	v_mad_i64_i32 v[2:3], s[16:17], v6, s41, v[2:3]
	v_and_b32_e32 v190, 0x70, v5
	v_lshl_add_u64 v[130:131], v[2:3], 0, v[190:191]
	v_add_u32_e32 v2, s39, v4
	v_min_i32_e32 v3, 0x3ff, v2
	v_mov_b64_e32 v[6:7], s[2:3]
	v_mad_i64_i32 v[4:5], s[16:17], v3, s41, 0
	v_mad_i64_i32 v[8:9], s[16:17], v3, s41, v[6:7]
	v_min_i32_e32 v3, 0x3bf, v2
	v_add_u32_e32 v3, 64, v3
	v_mad_i64_i32 v[10:11], s[16:17], v3, s41, v[6:7]
	v_min_i32_e32 v3, 0x37f, v2
	v_add_u32_e32 v3, 0x80, v3
	v_mad_i64_i32 v[12:13], s[16:17], v3, s41, v[6:7]
	v_min_i32_e32 v3, 0x33f, v2
	v_ashrrev_i32_e32 v14, 6, v16
	v_add_u32_e32 v3, 0xc0, v3
	v_mad_i64_i32 v[6:7], s[16:17], v3, s41, v[6:7]
	v_lshl_add_u32 v145, v14, 10, 0
	v_add_u32_e32 v3, 0x2000, v145
	v_readfirstlane_b32 s16, v145
	s_mov_b32 m0, s16
	s_mov_b64 s[16:17], 0x58000
	v_and_b32_e32 v143, 3, v14
	v_lshl_add_u64 v[14:15], v[130:131], 0, s[16:17]
	v_readfirstlane_b32 s16, v3
	s_barrier
	global_load_lds_dwordx4 v[130:131], off
	s_mov_b32 m0, s16
	s_mov_b64 s[16:17], 0xb0000
	v_add_u32_e32 v3, 0x4000, v145
	global_load_lds_dwordx4 v[14:15], off
	v_lshl_add_u64 v[14:15], v[130:131], 0, s[16:17]
	v_readfirstlane_b32 s16, v3
	s_mov_b32 m0, s16
	s_mov_b64 s[16:17], 0x108000
	v_add_u32_e32 v3, 0x6000, v145
	global_load_lds_dwordx4 v[14:15], off
	v_lshl_add_u64 v[14:15], v[130:131], 0, s[16:17]
	v_readfirstlane_b32 s16, v3
	v_add_u32_e32 v3, 0x8000, v145
	s_mov_b32 m0, s16
	v_readfirstlane_b32 s16, v3
	v_add_u32_e32 v3, 0xa000, v145
	v_lshl_add_u64 v[8:9], v[8:9], 0, v[190:191]
	global_load_lds_dwordx4 v[14:15], off
	s_mov_b32 m0, s16
	v_readfirstlane_b32 s16, v3
	v_add_u32_e32 v3, 0xc000, v145
	v_lshl_add_u64 v[10:11], v[10:11], 0, v[190:191]
	global_load_lds_dwordx4 v[8:9], off
	s_mov_b32 m0, s16
	v_readfirstlane_b32 s16, v3
	v_add_u32_e32 v3, 0xe000, v145
	v_lshl_add_u64 v[12:13], v[12:13], 0, v[190:191]
	global_load_lds_dwordx4 v[10:11], off
	s_mov_b32 m0, s16
	v_readfirstlane_b32 s16, v3
	v_lshl_add_u64 v[6:7], v[6:7], 0, v[190:191]
	global_load_lds_dwordx4 v[12:13], off
	s_mov_b32 m0, s16
	v_and_b32_e32 v142, 15, v16
	global_load_lds_dwordx4 v[6:7], off
	v_ashrrev_i32_e32 v140, 8, v16
	v_bfe_u32 v141, v16, 4, 2
	v_bfe_u32 v3, v16, 1, 3
	v_lshlrev_b32_e32 v6, 7, v142
	v_lshl_or_b32 v148, v140, 14, v6
	v_lshl_or_b32 v147, v143, 13, v6
	v_bitop3_b32 v6, v17, v3, 3 bitop3:0x6c
	v_bitop3_b32 v3, v141, v3, 4 bitop3:0x36
	v_lshlrev_b32_e32 v144, 4, v3
	v_ashrrev_i32_e32 v3, 31, v2
	s_mov_b64 s[16:17], 0x33f
	v_cmp_gt_i64_e32 vcc, s[16:17], v[2:3]
	v_lshlrev_b32_e32 v146, 4, v6
	v_bitop3_b32 v8, v17, 7, v16 bitop3:0x48
	v_cndmask_b32_e32 v6, v227, v2, vcc
	v_mad_i64_i32 v[6:7], s[16:17], v6, s41, 0
	v_lshlrev_b32_e32 v8, 4, v8
	s_mov_b64 s[16:17], 0x37f
	v_or_b32_e32 v6, v6, v8
	v_cmp_gt_i64_e32 vcc, s[16:17], v[2:3]
	v_lshl_add_u64 v[132:133], s[8:9], 0, v[6:7]
	s_waitcnt vmcnt(0)
	v_or_b32_e32 v4, v4, v8
	v_cndmask_b32_e32 v6, v197, v2, vcc
	v_mad_i64_i32 v[6:7], s[16:17], v6, s41, 0
	s_mov_b64 s[16:17], 0x3bf
	s_nop 0
	v_cmp_gt_i64_e32 vcc, s[16:17], v[2:3]
	v_or_b32_e32 v6, v6, v8
	v_lshl_add_u64 v[134:135], s[10:11], 0, v[6:7]
	v_cndmask_b32_e32 v2, v195, v2, vcc
	v_mad_i64_i32 v[2:3], s[16:17], v2, s41, 0
	v_or_b32_e32 v2, v2, v8
	v_lshl_add_u64 v[136:137], s[12:13], 0, v[2:3]
	v_mov_b32_e32 v2, 0
	v_lshl_add_u64 v[138:139], s[14:15], 0, v[4:5]
	s_mov_b64 s[16:17], 0
	s_mov_b32 s41, 0
	v_mov_b32_e32 v3, v2
	v_mov_b32_e32 v4, v2
	v_mov_b32_e32 v5, v2
	v_mov_b32_e32 v6, v2
	v_mov_b32_e32 v7, v2
	v_mov_b32_e32 v8, v2
	v_mov_b32_e32 v9, v2
	v_mov_b32_e32 v10, v2
	v_mov_b32_e32 v11, v2
	v_mov_b32_e32 v12, v2
	v_mov_b32_e32 v13, v2
	v_mov_b32_e32 v14, v2
	v_mov_b32_e32 v15, v2
	v_mov_b32_e32 v16, v2
	v_mov_b32_e32 v17, v2
	v_mov_b32_e32 v18, v2
	v_mov_b32_e32 v19, v2
	v_mov_b32_e32 v20, v2
	v_mov_b32_e32 v21, v2
	v_mov_b32_e32 v22, v2
	v_mov_b32_e32 v23, v2
	v_mov_b32_e32 v24, v2
	v_mov_b32_e32 v25, v2
	v_mov_b32_e32 v26, v2
	v_mov_b32_e32 v27, v2
	v_mov_b32_e32 v28, v2
	v_mov_b32_e32 v29, v2
	v_mov_b32_e32 v30, v2
	v_mov_b32_e32 v31, v2
	v_mov_b32_e32 v32, v2
	v_mov_b32_e32 v33, v2
	v_mov_b32_e32 v34, v2
	v_mov_b32_e32 v35, v2
	v_mov_b32_e32 v36, v2
	v_mov_b32_e32 v37, v2
	v_mov_b32_e32 v38, v2
	v_mov_b32_e32 v39, v2
	v_mov_b32_e32 v40, v2
	v_mov_b32_e32 v41, v2
	v_mov_b32_e32 v42, v2
	v_mov_b32_e32 v43, v2
	v_mov_b32_e32 v44, v2
	v_mov_b32_e32 v45, v2
	v_mov_b32_e32 v46, v2
	v_mov_b32_e32 v47, v2
	v_mov_b32_e32 v48, v2
	v_mov_b32_e32 v49, v2
	v_mov_b32_e32 v50, v2
	v_mov_b32_e32 v51, v2
	v_mov_b32_e32 v52, v2
	v_mov_b32_e32 v53, v2
	v_mov_b32_e32 v54, v2
	v_mov_b32_e32 v55, v2
	v_mov_b32_e32 v56, v2
	v_mov_b32_e32 v57, v2
	v_mov_b32_e32 v58, v2
	v_mov_b32_e32 v59, v2
	v_mov_b32_e32 v60, v2
	v_mov_b32_e32 v61, v2
	v_mov_b32_e32 v62, v2
	v_mov_b32_e32 v63, v2
	v_mov_b32_e32 v64, v2
	v_mov_b32_e32 v65, v2
	v_mov_b32_e32 v66, v2
	v_mov_b32_e32 v67, v2
	v_mov_b32_e32 v68, v2
	v_mov_b32_e32 v69, v2
	v_mov_b32_e32 v70, v2
	v_mov_b32_e32 v71, v2
	v_mov_b32_e32 v72, v2
	v_mov_b32_e32 v73, v2
	v_mov_b32_e32 v74, v2
	v_mov_b32_e32 v75, v2
	v_mov_b32_e32 v76, v2
	v_mov_b32_e32 v77, v2
	v_mov_b32_e32 v78, v2
	v_mov_b32_e32 v79, v2
	v_mov_b32_e32 v80, v2
	v_mov_b32_e32 v81, v2
	s_waitcnt vmcnt(0)
; #define MFMA16(a, b, c) __builtin_amdgcn_mfma_f32_16x16x32_bf16((a), (b), (c), 0, 0, 0)
;     ...
;   f32x4 acc[MT][4];
; #pragma unroll
;   for (int a = 0; a < MT; ++a)
; #pragma unroll
;     for (int b = 0; b < 4; ++b) { acc[a][b][0] = 0.f; acc[a][b][1] = 0.f; acc[a][b][2] = 0.f; acc[a][b][3] = 0.f; }
;     ...
;   for (int kt = 0; kt < nk; ++kt) {
;     const int buf = kt & 1;
;     const char* cA = smem + buf * STAGE + (wm * 32 * MI + r16) * 128;
;     const char* cB = smem + buf * STAGE + 32768 + (wn * 64 + r16) * 128;
; #pragma unroll
;     for (int k2 = 0; k2 < 2; ++k2) {
;       if (k2 == 1 && kt + 1 < nk) STAGE_TILE(buf ^ 1, (kt + 1) * 64)
;       const int po = ((4 * k2 + q4) ^ swz) * 16;
;       bf16x8 bf[4];
; #pragma unroll
;       for (int nt = 0; nt < 4; ++nt) bf[nt] = *(const bf16x8*)(cB + nt * 16 * 128 + po);
;       bf16x8 afc = *(const bf16x8*)(cA + po);
; #pragma unroll
;       for (int a = 0; a < MT; ++a) {
;         bf16x8 afn = afc;
;         if (a + 1 < MT) afn = *(const bf16x8*)(cA + (a + 1) * 16 * 128 + po);
;         __builtin_amdgcn_sched_barrier(0);
; #pragma unroll
;         for (int nt = 0; nt < 4; ++nt) acc[a][nt] = MFMA16(bf[nt], afc, acc[a][nt]);
;         __builtin_amdgcn_sched_barrier(0);
;         afc = afn;
;       }
	v_mov_b32_e32 v82, v2
	v_mov_b32_e32 v83, v2
	v_mov_b32_e32 v84, v2
	v_mov_b32_e32 v85, v2
	v_mov_b32_e32 v86, v2
	v_mov_b32_e32 v87, v2
	v_mov_b32_e32 v88, v2
	v_mov_b32_e32 v89, v2
	v_mov_b32_e32 v90, v2
	v_mov_b32_e32 v91, v2
	v_mov_b32_e32 v92, v2
	v_mov_b32_e32 v93, v2
	v_mov_b32_e32 v94, v2
	v_mov_b32_e32 v95, v2
	v_mov_b32_e32 v96, v2
	v_mov_b32_e32 v97, v2
	v_mov_b32_e32 v98, v2
	v_mov_b32_e32 v99, v2
	v_mov_b32_e32 v100, v2
	v_mov_b32_e32 v101, v2
	v_mov_b32_e32 v102, v2
	v_mov_b32_e32 v103, v2
	v_mov_b32_e32 v104, v2
	v_mov_b32_e32 v105, v2
	v_mov_b32_e32 v106, v2
	v_mov_b32_e32 v107, v2
	v_mov_b32_e32 v108, v2
	v_mov_b32_e32 v109, v2
	v_mov_b32_e32 v110, v2
	v_mov_b32_e32 v111, v2
	v_mov_b32_e32 v112, v2
	v_mov_b32_e32 v113, v2
	v_mov_b32_e32 v114, v2
	v_mov_b32_e32 v115, v2
	v_mov_b32_e32 v116, v2
	v_mov_b32_e32 v117, v2
	v_mov_b32_e32 v118, v2
	v_mov_b32_e32 v119, v2
	v_mov_b32_e32 v120, v2
	v_mov_b32_e32 v121, v2
	v_mov_b32_e32 v122, v2
	v_mov_b32_e32 v123, v2
	v_mov_b32_e32 v124, v2
	v_mov_b32_e32 v125, v2
	v_mov_b32_e32 v126, v2
	v_mov_b32_e32 v127, v2
	v_mov_b32_e32 v128, v2
	v_mov_b32_e32 v129, v2
	v_readlane_b32 s53, v253, 41
	v_readlane_b32 s56, v253, 44
	v_readlane_b32 s57, v253, 45
	v_readlane_b32 s58, v253, 46
	v_readlane_b32 s59, v253, 47
	v_readlane_b32 s60, v253, 48
	v_readlane_b32 s61, v253, 49
	v_readlane_b32 s62, v253, 50
	v_readlane_b32 s63, v253, 51
	v_readlane_b32 s64, v253, 52
	v_readlane_b32 s65, v253, 53
	v_readlane_b32 s66, v253, 54
	v_readlane_b32 s67, v253, 55
	s_waitcnt vmcnt(0) lgkmcnt(0)
	s_barrier
	v_readfirstlane_b32 s100, v138
	v_readfirstlane_b32 s101, v139
	s_nop 0
	s_sub_u32 s100, s100, 0x80
	s_subb_u32 s101, s101, 0
	v_add_u32_e32 v176, s24, v130
	v_subrev_u32_e32 v176, s100, v176
	v_add_u32_e32 v177, 0x58080, v130
	v_subrev_u32_e32 v177, s100, v177
	v_add_u32_e32 v178, 0xb0080, v130
	v_subrev_u32_e32 v178, s100, v178
	v_add_u32_e32 v179, 0x108080, v130
	v_subrev_u32_e32 v179, s100, v179
	v_subrev_u32_e32 v180, s100, v138
	v_subrev_u32_e32 v181, s100, v136
	v_subrev_u32_e32 v182, s100, v134
	v_subrev_u32_e32 v183, s100, v132
.LBB0_48:
	s_and_b32 s42, s41, 0x10000
	s_add_i32 s43, s42, 0
	v_add_u32_e32 v174, s43, v147
	v_add_u32_e32 v162, v174, v146
	v_add_u32_e32 v149, s43, v148
	ds_read_b128 v[150:153], v162 offset:32768
	ds_read_b128 v[154:157], v162 offset:34816
	ds_read_b128 v[158:161], v162 offset:36864
	ds_read_b128 v[162:165], v162 offset:38912
	v_add_u32_e32 v175, v149, v146
	ds_read_b128 v[166:169], v175
	ds_read_b128 v[170:173], v175 offset:2048
	s_waitcnt lgkmcnt(1)
	v_mfma_f32_16x16x32_bf16 v[126:129], v[150:153], v[166:169], v[126:129]
	v_mfma_f32_16x16x32_bf16 v[122:125], v[154:157], v[166:169], v[122:125]
	v_mfma_f32_16x16x32_bf16 v[118:121], v[158:161], v[166:169], v[118:121]
	v_mfma_f32_16x16x32_bf16 v[114:117], v[162:165], v[166:169], v[114:117]
	ds_read_b128 v[166:169], v175 offset:4096
	s_waitcnt lgkmcnt(1)
	v_mfma_f32_16x16x32_bf16 v[110:113], v[150:153], v[170:173], v[110:113]
	v_mfma_f32_16x16x32_bf16 v[106:109], v[154:157], v[170:173], v[106:109]
	v_mfma_f32_16x16x32_bf16 v[102:105], v[158:161], v[170:173], v[102:105]
	v_mfma_f32_16x16x32_bf16 v[98:101], v[162:165], v[170:173], v[98:101]
	ds_read_b128 v[170:173], v175 offset:6144
	s_waitcnt lgkmcnt(1)
	v_mfma_f32_16x16x32_bf16 v[94:97], v[150:153], v[166:169], v[94:97]
	v_mfma_f32_16x16x32_bf16 v[90:93], v[154:157], v[166:169], v[90:93]
	v_mfma_f32_16x16x32_bf16 v[86:89], v[158:161], v[166:169], v[86:89]
	v_mfma_f32_16x16x32_bf16 v[82:85], v[162:165], v[166:169], v[82:85]
	ds_read_b128 v[166:169], v175 offset:8192
	s_waitcnt lgkmcnt(1)
	v_mfma_f32_16x16x32_bf16 v[78:81], v[150:153], v[170:173], v[78:81]
	v_mfma_f32_16x16x32_bf16 v[74:77], v[154:157], v[170:173], v[74:77]
	v_mfma_f32_16x16x32_bf16 v[70:73], v[158:161], v[170:173], v[70:73]
	v_mfma_f32_16x16x32_bf16 v[66:69], v[162:165], v[170:173], v[66:69]
	ds_read_b128 v[170:173], v175 offset:10240
	s_waitcnt lgkmcnt(1)
	v_mfma_f32_16x16x32_bf16 v[62:65], v[150:153], v[166:169], v[62:65]
	v_mfma_f32_16x16x32_bf16 v[58:61], v[154:157], v[166:169], v[58:61]
	v_mfma_f32_16x16x32_bf16 v[54:57], v[158:161], v[166:169], v[54:57]
	v_mfma_f32_16x16x32_bf16 v[50:53], v[162:165], v[166:169], v[50:53]
	ds_read_b128 v[166:169], v175 offset:12288
	s_waitcnt lgkmcnt(1)
	v_mfma_f32_16x16x32_bf16 v[46:49], v[150:153], v[170:173], v[46:49]
	v_mfma_f32_16x16x32_bf16 v[42:45], v[154:157], v[170:173], v[42:45]
	v_mfma_f32_16x16x32_bf16 v[38:41], v[158:161], v[170:173], v[38:41]
	v_mfma_f32_16x16x32_bf16 v[34:37], v[162:165], v[170:173], v[34:37]
	ds_read_b128 v[170:173], v175 offset:14336
	s_waitcnt lgkmcnt(1)
	v_mfma_f32_16x16x32_bf16 v[30:33], v[150:153], v[166:169], v[30:33]
	v_mfma_f32_16x16x32_bf16 v[26:29], v[154:157], v[166:169], v[26:29]
	v_mfma_f32_16x16x32_bf16 v[22:25], v[158:161], v[166:169], v[22:25]
	v_mfma_f32_16x16x32_bf16 v[18:21], v[162:165], v[166:169], v[18:21]
	s_waitcnt lgkmcnt(0)
	v_mfma_f32_16x16x32_bf16 v[14:17], v[150:153], v[170:173], v[14:17]
	v_mfma_f32_16x16x32_bf16 v[10:13], v[154:157], v[170:173], v[10:13]
	v_mfma_f32_16x16x32_bf16 v[6:9], v[158:161], v[170:173], v[6:9]
	v_mfma_f32_16x16x32_bf16 v[2:5], v[162:165], v[170:173], v[2:5]
	s_xor_b32 s42, s42, 0x10000
	v_readfirstlane_b32 s43, v145
	s_nop 0
	s_add_u32 s43, s43, s42
	s_add_u32 m0, s43, 0x0
	s_nop 0
	global_load_lds_dwordx4 v176, s[100:101]
	s_add_u32 m0, s43, 0x2000
	s_nop 0
	global_load_lds_dwordx4 v177, s[100:101]
	s_add_u32 m0, s43, 0x4000
	s_nop 0
	global_load_lds_dwordx4 v178, s[100:101]
	s_add_u32 m0, s43, 0x6000
	s_nop 0
	global_load_lds_dwordx4 v179, s[100:101]
	s_add_u32 m0, s43, 0x8000
	s_nop 0
	global_load_lds_dwordx4 v180, s[100:101]
	s_add_u32 m0, s43, 0xa000
	s_nop 0
	global_load_lds_dwordx4 v181, s[100:101]
	s_add_u32 m0, s43, 0xc000
	s_nop 0
	global_load_lds_dwordx4 v182, s[100:101]
	s_add_u32 m0, s43, 0xe000
	s_nop 0
	global_load_lds_dwordx4 v183, s[100:101]
	v_add_u32_e32 v162, v174, v144
	ds_read_b128 v[150:153], v162 offset:32768
	ds_read_b128 v[154:157], v162 offset:34816
	ds_read_b128 v[158:161], v162 offset:36864
	ds_read_b128 v[162:165], v162 offset:38912
	v_add_u32_e32 v149, v149, v144
	ds_read_b128 v[166:169], v149
	ds_read_b128 v[170:173], v149 offset:2048
	s_waitcnt lgkmcnt(0)
; #define MFMA16(a, b, c) __builtin_amdgcn_mfma_f32_16x16x32_bf16((a), (b), (c), 0, 0, 0)
;     ...
;   for (int kt = 0; kt < nk; ++kt) {
;     const int buf = kt & 1;
;     const char* cA = smem + buf * STAGE + (wm * 32 * MI + r16) * 128;
;     const char* cB = smem + buf * STAGE + 32768 + (wn * 64 + r16) * 128;
; #pragma unroll
;     for (int k2 = 0; k2 < 2; ++k2) {
;       if (k2 == 1 && kt + 1 < nk) STAGE_TILE(buf ^ 1, (kt + 1) * 64)
;       const int po = ((4 * k2 + q4) ^ swz) * 16;
;       bf16x8 bf[4];
; #pragma unroll
;       for (int nt = 0; nt < 4; ++nt) bf[nt] = *(const bf16x8*)(cB + nt * 16 * 128 + po);
;       bf16x8 afc = *(const bf16x8*)(cA + po);
; #pragma unroll
;       for (int a = 0; a < MT; ++a) {
;         bf16x8 afn = afc;
;         if (a + 1 < MT) afn = *(const bf16x8*)(cA + (a + 1) * 16 * 128 + po);
;         __builtin_amdgcn_sched_barrier(0);
; #pragma unroll
;         for (int nt = 0; nt < 4; ++nt) acc[a][nt] = MFMA16(bf[nt], afc, acc[a][nt]);
;         __builtin_amdgcn_sched_barrier(0);
;         afc = afn;
;       }
;     }
;     asm volatile("s_waitcnt vmcnt(0)" ::: "memory");
;     __syncthreads();
;   }
	v_mfma_f32_16x16x32_bf16 v[126:129], v[150:153], v[166:169], v[126:129]
	v_mfma_f32_16x16x32_bf16 v[122:125], v[154:157], v[166:169], v[122:125]
	v_mfma_f32_16x16x32_bf16 v[118:121], v[158:161], v[166:169], v[118:121]
	v_mfma_f32_16x16x32_bf16 v[114:117], v[162:165], v[166:169], v[114:117]
	ds_read_b128 v[166:169], v149 offset:4096
	v_mfma_f32_16x16x32_bf16 v[110:113], v[150:153], v[170:173], v[110:113]
	v_mfma_f32_16x16x32_bf16 v[106:109], v[154:157], v[170:173], v[106:109]
	v_mfma_f32_16x16x32_bf16 v[102:105], v[158:161], v[170:173], v[102:105]
	v_mfma_f32_16x16x32_bf16 v[98:101], v[162:165], v[170:173], v[98:101]
	ds_read_b128 v[170:173], v149 offset:6144
	s_waitcnt lgkmcnt(0)
	v_mfma_f32_16x16x32_bf16 v[94:97], v[150:153], v[166:169], v[94:97]
	v_mfma_f32_16x16x32_bf16 v[90:93], v[154:157], v[166:169], v[90:93]
	v_mfma_f32_16x16x32_bf16 v[86:89], v[158:161], v[166:169], v[86:89]
	v_mfma_f32_16x16x32_bf16 v[82:85], v[162:165], v[166:169], v[82:85]
	ds_read_b128 v[166:169], v149 offset:8192
	v_mfma_f32_16x16x32_bf16 v[78:81], v[150:153], v[170:173], v[78:81]
	v_mfma_f32_16x16x32_bf16 v[74:77], v[154:157], v[170:173], v[74:77]
	v_mfma_f32_16x16x32_bf16 v[70:73], v[158:161], v[170:173], v[70:73]
	v_mfma_f32_16x16x32_bf16 v[66:69], v[162:165], v[170:173], v[66:69]
	ds_read_b128 v[170:173], v149 offset:10240
	s_waitcnt lgkmcnt(0)
	v_mfma_f32_16x16x32_bf16 v[62:65], v[150:153], v[166:169], v[62:65]
	v_mfma_f32_16x16x32_bf16 v[58:61], v[154:157], v[166:169], v[58:61]
	v_mfma_f32_16x16x32_bf16 v[54:57], v[158:161], v[166:169], v[54:57]
	v_mfma_f32_16x16x32_bf16 v[50:53], v[162:165], v[166:169], v[50:53]
	ds_read_b128 v[166:169], v149 offset:12288
	v_mfma_f32_16x16x32_bf16 v[46:49], v[150:153], v[170:173], v[46:49]
	v_mfma_f32_16x16x32_bf16 v[42:45], v[154:157], v[170:173], v[42:45]
	v_mfma_f32_16x16x32_bf16 v[38:41], v[158:161], v[170:173], v[38:41]
	v_mfma_f32_16x16x32_bf16 v[34:37], v[162:165], v[170:173], v[34:37]
	ds_read_b128 v[170:173], v149 offset:14336
	s_waitcnt lgkmcnt(0)
	v_mfma_f32_16x16x32_bf16 v[30:33], v[150:153], v[166:169], v[30:33]
	v_mfma_f32_16x16x32_bf16 v[26:29], v[154:157], v[166:169], v[26:29]
	v_mfma_f32_16x16x32_bf16 v[22:25], v[158:161], v[166:169], v[22:25]
	v_mfma_f32_16x16x32_bf16 v[18:21], v[162:165], v[166:169], v[18:21]
	v_mfma_f32_16x16x32_bf16 v[14:17], v[150:153], v[170:173], v[14:17]
	v_mfma_f32_16x16x32_bf16 v[10:13], v[154:157], v[170:173], v[10:13]
	v_mfma_f32_16x16x32_bf16 v[6:9], v[158:161], v[170:173], v[6:9]
	v_mfma_f32_16x16x32_bf16 v[2:5], v[162:165], v[170:173], v[2:5]
	s_waitcnt vmcnt(0)
	s_add_u32 s100, s100, 0x80
	s_addc_u32 s101, s101, 0
	s_add_u32 s16, s16, 0x80
	s_addc_u32 s17, s17, 0
	s_add_i32 s41, s41, 0x10000
	s_cmpk_eq_i32 s16, 0x1580
	s_waitcnt vmcnt(0)
	s_barrier
	s_cbranch_scc0 .LBB0_48
	s_add_i32 s16, 0, 0x10000
	v_add_u32_e32 v138, s16, v148
	v_readlane_b32 s16, v254, 18
	s_nop 1
	v_add_u32_e32 v139, s16, v147
	v_add_u32_e32 v145, v139, v146
	ds_read_b128 v[130:133], v145
	ds_read_b128 v[134:137], v145 offset:2048
	ds_read_b128 v[148:151], v145 offset:4096
	ds_read_b128 v[152:155], v145 offset:6144
	v_add_u32_e32 v145, v138, v146
	ds_read_b128 v[156:159], v145
	ds_read_b128 v[160:163], v145 offset:2048
	s_waitcnt lgkmcnt(1)
	v_mfma_f32_16x16x32_bf16 v[126:129], v[130:133], v[156:159], v[126:129]
	v_mfma_f32_16x16x32_bf16 v[122:125], v[134:137], v[156:159], v[122:125]
	v_mfma_f32_16x16x32_bf16 v[118:121], v[148:151], v[156:159], v[118:121]
	v_mfma_f32_16x16x32_bf16 v[114:117], v[152:155], v[156:159], v[114:117]
	ds_read_b128 v[156:159], v145 offset:4096
	s_waitcnt lgkmcnt(1)
	v_mfma_f32_16x16x32_bf16 v[110:113], v[130:133], v[160:163], v[110:113]
	v_mfma_f32_16x16x32_bf16 v[106:109], v[134:137], v[160:163], v[106:109]
	v_mfma_f32_16x16x32_bf16 v[102:105], v[148:151], v[160:163], v[102:105]
	v_mfma_f32_16x16x32_bf16 v[98:101], v[152:155], v[160:163], v[98:101]
	ds_read_b128 v[160:163], v145 offset:6144
	s_waitcnt lgkmcnt(1)
	v_mfma_f32_16x16x32_bf16 v[94:97], v[130:133], v[156:159], v[94:97]
	v_mfma_f32_16x16x32_bf16 v[90:93], v[134:137], v[156:159], v[90:93]
	v_mfma_f32_16x16x32_bf16 v[86:89], v[148:151], v[156:159], v[86:89]
	v_mfma_f32_16x16x32_bf16 v[82:85], v[152:155], v[156:159], v[82:85]
	ds_read_b128 v[156:159], v145 offset:8192
	s_waitcnt lgkmcnt(1)
	v_mfma_f32_16x16x32_bf16 v[78:81], v[130:133], v[160:163], v[78:81]
	v_mfma_f32_16x16x32_bf16 v[74:77], v[134:137], v[160:163], v[74:77]
	v_mfma_f32_16x16x32_bf16 v[70:73], v[148:151], v[160:163], v[70:73]
	v_mfma_f32_16x16x32_bf16 v[66:69], v[152:155], v[160:163], v[66:69]
	ds_read_b128 v[160:163], v145 offset:10240
	s_waitcnt lgkmcnt(1)
	v_mfma_f32_16x16x32_bf16 v[62:65], v[130:133], v[156:159], v[62:65]
	v_mfma_f32_16x16x32_bf16 v[58:61], v[134:137], v[156:159], v[58:61]
	v_mfma_f32_16x16x32_bf16 v[54:57], v[148:151], v[156:159], v[54:57]
	v_mfma_f32_16x16x32_bf16 v[50:53], v[152:155], v[156:159], v[50:53]
	ds_read_b128 v[156:159], v145 offset:12288
	s_waitcnt lgkmcnt(1)
	v_mfma_f32_16x16x32_bf16 v[46:49], v[130:133], v[160:163], v[46:49]
	v_mfma_f32_16x16x32_bf16 v[42:45], v[134:137], v[160:163], v[42:45]
	v_mfma_f32_16x16x32_bf16 v[38:41], v[148:151], v[160:163], v[38:41]
	v_mfma_f32_16x16x32_bf16 v[34:37], v[152:155], v[160:163], v[34:37]
	ds_read_b128 v[160:163], v145 offset:14336
	s_waitcnt lgkmcnt(1)
	v_mfma_f32_16x16x32_bf16 v[30:33], v[130:133], v[156:159], v[30:33]
	v_mfma_f32_16x16x32_bf16 v[26:29], v[134:137], v[156:159], v[26:29]
	v_mfma_f32_16x16x32_bf16 v[22:25], v[148:151], v[156:159], v[22:25]
	v_mfma_f32_16x16x32_bf16 v[18:21], v[152:155], v[156:159], v[18:21]
	s_waitcnt lgkmcnt(0)
; #define MFMA16(a, b, c) __builtin_amdgcn_mfma_f32_16x16x32_bf16((a), (b), (c), 0, 0, 0)
;     ...
; #pragma unroll
;     for (int k2 = 0; k2 < 2; ++k2) {
;       if (k2 == 1 && kt + 1 < nk) STAGE_TILE(buf ^ 1, (kt + 1) * 64)
;       const int po = ((4 * k2 + q4) ^ swz) * 16;
;       bf16x8 bf[4];
; #pragma unroll
;       for (int nt = 0; nt < 4; ++nt) bf[nt] = *(const bf16x8*)(cB + nt * 16 * 128 + po);
;       bf16x8 afc = *(const bf16x8*)(cA + po);
; #pragma unroll
;       for (int a = 0; a < MT; ++a) {
;         bf16x8 afn = afc;
;         if (a + 1 < MT) afn = *(const bf16x8*)(cA + (a + 1) * 16 * 128 + po);
;         __builtin_amdgcn_sched_barrier(0);
; #pragma unroll
;         for (int nt = 0; nt < 4; ++nt) acc[a][nt] = MFMA16(bf[nt], afc, acc[a][nt]);
;         __builtin_amdgcn_sched_barrier(0);
;         afc = afn;
;       }
; DI void phase_resid(char* smem, const Params& p, int layer, const bf16_t* A, int K, const bf16_t* W, int gate_idx, bool first) {
;     ...
;   auto ep = [&](int row, int col, float v0, float v1, float v2, float v3) {
;     const int b = row / TT, t = row - b * TT;
;     const float4 g = *(const float4*)(p.mod + (size_t)(layer * 5 + (t < CTXL ? 4 : b)) * 6144 + gate_idx * 1024 + col);
;     const float4 xo = *(const float4*)(xsrc_row(p, first, row) + col);
	v_mfma_f32_16x16x32_bf16 v[14:17], v[130:133], v[160:163], v[14:17]
	v_mfma_f32_16x16x32_bf16 v[10:13], v[134:137], v[160:163], v[10:13]
	v_mfma_f32_16x16x32_bf16 v[6:9], v[148:151], v[160:163], v[6:9]
	v_mfma_f32_16x16x32_bf16 v[2:5], v[152:155], v[160:163], v[2:5]
	v_add_u32_e32 v139, v139, v144
	ds_read_b128 v[130:133], v139
	ds_read_b128 v[134:137], v139 offset:2048
	ds_read_b128 v[146:149], v139 offset:4096
	ds_read_b128 v[150:153], v139 offset:6144
	v_add_u32_e32 v138, v138, v144
	ds_read_b128 v[154:157], v138
	ds_read_b128 v[158:161], v138 offset:2048
	s_waitcnt lgkmcnt(1)
	v_mfma_f32_16x16x32_bf16 v[126:129], v[130:133], v[154:157], v[126:129]
	v_mfma_f32_16x16x32_bf16 v[122:125], v[134:137], v[154:157], v[122:125]
	v_mfma_f32_16x16x32_bf16 v[118:121], v[146:149], v[154:157], v[118:121]
	v_mfma_f32_16x16x32_bf16 v[114:117], v[150:153], v[154:157], v[114:117]
	ds_read_b128 v[154:157], v138 offset:4096
	s_waitcnt lgkmcnt(1)
	v_mfma_f32_16x16x32_bf16 v[110:113], v[130:133], v[158:161], v[110:113]
	v_mfma_f32_16x16x32_bf16 v[106:109], v[134:137], v[158:161], v[106:109]
	v_mfma_f32_16x16x32_bf16 v[102:105], v[146:149], v[158:161], v[102:105]
	v_mfma_f32_16x16x32_bf16 v[98:101], v[150:153], v[158:161], v[98:101]
	ds_read_b128 v[158:161], v138 offset:6144
	s_waitcnt lgkmcnt(1)
	v_mfma_f32_16x16x32_bf16 v[94:97], v[130:133], v[154:157], v[94:97]
	v_mfma_f32_16x16x32_bf16 v[90:93], v[134:137], v[154:157], v[90:93]
	v_mfma_f32_16x16x32_bf16 v[86:89], v[146:149], v[154:157], v[86:89]
	v_mfma_f32_16x16x32_bf16 v[82:85], v[150:153], v[154:157], v[82:85]
	ds_read_b128 v[154:157], v138 offset:8192
	s_waitcnt lgkmcnt(1)
	v_mfma_f32_16x16x32_bf16 v[78:81], v[130:133], v[158:161], v[78:81]
	v_mfma_f32_16x16x32_bf16 v[74:77], v[134:137], v[158:161], v[74:77]
	v_mfma_f32_16x16x32_bf16 v[70:73], v[146:149], v[158:161], v[70:73]
	v_mfma_f32_16x16x32_bf16 v[66:69], v[150:153], v[158:161], v[66:69]
	ds_read_b128 v[158:161], v138 offset:10240
	s_waitcnt lgkmcnt(1)
	v_mfma_f32_16x16x32_bf16 v[62:65], v[130:133], v[154:157], v[62:65]
	v_mfma_f32_16x16x32_bf16 v[58:61], v[134:137], v[154:157], v[58:61]
	v_mfma_f32_16x16x32_bf16 v[54:57], v[146:149], v[154:157], v[54:57]
	v_mfma_f32_16x16x32_bf16 v[50:53], v[150:153], v[154:157], v[50:53]
	ds_read_b128 v[154:157], v138 offset:12288
	s_waitcnt lgkmcnt(1)
	v_mfma_f32_16x16x32_bf16 v[46:49], v[130:133], v[158:161], v[46:49]
	v_mfma_f32_16x16x32_bf16 v[42:45], v[134:137], v[158:161], v[42:45]
	v_mfma_f32_16x16x32_bf16 v[38:41], v[146:149], v[158:161], v[38:41]
	v_mfma_f32_16x16x32_bf16 v[34:37], v[150:153], v[158:161], v[34:37]
	ds_read_b128 v[158:161], v138 offset:14336
	s_waitcnt lgkmcnt(1)
	v_mfma_f32_16x16x32_bf16 v[30:33], v[130:133], v[154:157], v[30:33]
	v_mfma_f32_16x16x32_bf16 v[26:29], v[134:137], v[154:157], v[26:29]
	v_mfma_f32_16x16x32_bf16 v[22:25], v[146:149], v[154:157], v[22:25]
	v_mfma_f32_16x16x32_bf16 v[18:21], v[150:153], v[154:157], v[18:21]
	s_waitcnt lgkmcnt(0)
	v_mfma_f32_16x16x32_bf16 v[14:17], v[130:133], v[158:161], v[14:17]
	v_mfma_f32_16x16x32_bf16 v[10:13], v[134:137], v[158:161], v[10:13]
	v_mfma_f32_16x16x32_bf16 v[6:9], v[146:149], v[158:161], v[6:9]
	v_mfma_f32_16x16x32_bf16 v[2:5], v[150:153], v[158:161], v[2:5]
	v_or_b32_e32 v131, s40, v142
	v_lshlrev_b32_e32 v130, 6, v143
	v_lshl_add_u32 v142, v140, 7, v131
	v_lshlrev_b32_e32 v131, 2, v141
	v_or3_b32 v134, v130, v131, s39
	v_mul_hi_i32 v130, v142, s1
	v_lshrrev_b32_e32 v131, 31, v130
	v_ashrrev_i32_e32 v130, 11, v130
	v_add_u32_e32 v130, v130, v131
	v_mad_i32_i24 v131, v130, s90, v142
	s_movk_i32 s39, 0x100
	v_cmp_gt_i32_e32 vcc, s39, v131
	v_add_u32_e32 v132, 0xffffff00, v131
	v_ashrrev_i32_e32 v133, 31, v131
	v_readlane_b32 s40, v254, 1
	v_cndmask_b32_e64 v135, v130, 4, vcc
	v_cndmask_b32_e32 v133, 0, v133, vcc
	v_cndmask_b32_e32 v132, v132, v131, vcc
	v_ashrrev_i32_e32 v131, 31, v130
	v_cndmask_b32_e64 v136, 25, 20, vcc
	v_readlane_b32 s41, v254, 2
	v_lshlrev_b64 v[140:141], v136, v[130:131]
	v_lshlrev_b64 v[150:151], 12, v[132:133]
	v_add_u32_e32 v130, s37, v135
	v_mov_b64_e32 v[132:133], s[40:41]
	s_movk_i32 s40, 0x6000
	v_readlane_b32 s42, v254, 3
	v_readlane_b32 s43, v254, 4
	v_mad_i64_i32 v[130:131], s[16:17], v130, s40, v[132:133]
	s_mov_b64 s[42:43], 0x5000
	v_ashrrev_i32_e32 v135, 31, v134
	v_readlane_b32 s16, v252, 26
	v_lshl_add_u64 v[136:137], v[130:131], 0, s[42:43]
	v_lshlrev_b64 v[130:131], 2, v[134:135]
	v_mov_b32_e32 v135, s16
	v_readlane_b32 s16, v252, 28
	s_waitcnt vmcnt(0)
	s_barrier
; DI void phase_resid(char* smem, const Params& p, int layer, const bf16_t* A, int K, const bf16_t* W, int gate_idx, bool first) {
;     ...
;   auto ep = [&](int row, int col, float v0, float v1, float v2, float v3) {
;     const int b = row / TT, t = row - b * TT;
;     const float4 g = *(const float4*)(p.mod + (size_t)(layer * 5 + (t < CTXL ? 4 : b)) * 6144 + gate_idx * 1024 + col);
;     const float4 xo = *(const float4*)(xsrc_row(p, first, row) + col);
;     *(float4*)(xdst_row(p, row) + col) = make_float4(xo.x + g.x * v0, xo.y + g.y * v1, xo.z + g.z * v2, xo.w + g.w * v3);
;   };
	s_nop 0
	v_mov_b32_e32 v143, s16
	v_readlane_b32 s16, v252, 25
	v_cndmask_b32_e32 v139, v135, v143, vcc
	s_nop 0
	v_mov_b32_e32 v144, s16
	v_readlane_b32 s16, v252, 27
	v_readlane_b32 s68, v252, 5
	v_readlane_b32 s80, v252, 17
	v_mov_b32_e32 v145, s16
	v_cndmask_b32_e32 v138, v144, v145, vcc
	global_load_dwordx2 v[138:139], v[138:139], off
	v_readlane_b32 s81, v252, 18
	v_readlane_b32 s82, v252, 19
	v_readlane_b32 s83, v252, 20
	v_mov_b32_e32 v146, s81
	v_mov_b32_e32 v148, s80
	v_mov_b32_e32 v147, s83
	v_mov_b32_e32 v149, s82
	v_cndmask_b32_e32 v155, v146, v147, vcc
	v_cndmask_b32_e32 v154, v148, v149, vcc
	v_lshl_add_u64 v[152:153], v[136:137], 0, v[130:131]
	s_add_i32 s38, s38, s30
	s_cmp_gt_i32 s38, 31
	v_readlane_b32 s44, v254, 5
	v_readlane_b32 s45, v254, 6
	v_readlane_b32 s46, v254, 7
	v_readlane_b32 s47, v254, 8
	v_readlane_b32 s48, v254, 9
	v_readlane_b32 s49, v254, 10
	v_readlane_b32 s50, v254, 11
	v_readlane_b32 s51, v254, 12
	v_readlane_b32 s52, v254, 13
	v_readlane_b32 s53, v254, 14
	v_readlane_b32 s54, v254, 15
	v_readlane_b32 s55, v254, 16
	v_readlane_b32 s69, v252, 6
	v_readlane_b32 s70, v252, 7
	v_readlane_b32 s71, v252, 8
	v_readlane_b32 s72, v252, 9
	v_readlane_b32 s73, v252, 10
	v_readlane_b32 s74, v252, 11
	v_readlane_b32 s75, v252, 12
	v_readlane_b32 s76, v252, 13
	v_readlane_b32 s77, v252, 14
	v_readlane_b32 s78, v252, 15
	v_readlane_b32 s79, v252, 16
	s_waitcnt vmcnt(0)
	v_lshl_add_u64 v[138:139], v[138:139], 0, v[140:141]
	v_lshl_add_u64 v[138:139], v[138:139], 0, v[150:151]
	v_lshl_add_u64 v[140:141], v[154:155], 0, v[140:141]
	v_lshl_add_u64 v[138:139], v[138:139], 0, v[130:131]
	v_lshl_add_u64 v[140:141], v[140:141], 0, v[150:151]
	v_lshl_add_u64 v[140:141], v[140:141], 0, v[130:131]
	s_cselect_b64 s[16:17], -1, 0
	global_load_dwordx4 v[156:159], v[152:153], off
	global_load_dwordx4 v[160:163], v[152:153], off offset:64
	global_load_dwordx4 v[164:167], v[152:153], off offset:128
	global_load_dwordx4 v[168:171], v[152:153], off offset:192
	global_load_dwordx4 v[172:175], v[138:139], off
	global_load_dwordx4 v[176:179], v[138:139], off offset:64
	global_load_dwordx4 v[180:183], v[138:139], off offset:128
	global_load_dwordx4 v[184:187], v[138:139], off offset:192
	v_add_co_u32_e32 v138, vcc, 0x10000, v138
	s_nop 1
	v_addc_co_u32_e32 v139, vcc, 0, v139, vcc
	global_load_dwordx4 v[198:201], v[138:139], off
	global_load_dwordx4 v[202:205], v[138:139], off offset:64
	global_load_dwordx4 v[206:209], v[138:139], off offset:128
	global_load_dwordx4 v[210:213], v[138:139], off offset:192
	v_add_co_u32_e32 v138, vcc, 0x10000, v138
	s_nop 1
	v_addc_co_u32_e32 v139, vcc, 0, v139, vcc
	global_load_dwordx4 v[214:217], v[138:139], off
	global_load_dwordx4 v[218:221], v[138:139], off offset:64
	global_load_dwordx4 v[222:225], v[138:139], off offset:128
	global_load_dwordx4 v[142:145], v[138:139], off offset:192
	v_add_co_u32_e32 v138, vcc, 0x10000, v138
	s_nop 1
	v_addc_co_u32_e32 v139, vcc, 0, v139, vcc
	s_waitcnt vmcnt(8)
	v_pk_fma_f32 v[126:127], v[126:127], v[156:157], v[172:173]
	v_pk_fma_f32 v[128:129], v[128:129], v[158:159], v[174:175]
	v_pk_fma_f32 v[122:123], v[122:123], v[160:161], v[176:177]
	v_pk_fma_f32 v[124:125], v[124:125], v[162:163], v[178:179]
	v_pk_fma_f32 v[118:119], v[118:119], v[164:165], v[180:181]
	v_pk_fma_f32 v[120:121], v[120:121], v[166:167], v[182:183]
	v_pk_fma_f32 v[114:115], v[114:115], v[168:169], v[184:185]
	v_pk_fma_f32 v[116:117], v[116:117], v[170:171], v[186:187]
	global_store_dwordx4 v[140:141], v[126:129], off
	global_store_dwordx4 v[140:141], v[122:125], off offset:64
	global_store_dwordx4 v[140:141], v[118:121], off offset:128
	global_store_dwordx4 v[140:141], v[114:117], off offset:192
	v_add_co_u32_e32 v140, vcc, 0x10000, v140
	s_nop 1
	v_addc_co_u32_e32 v141, vcc, 0, v141, vcc
	global_load_dwordx4 v[172:175], v[138:139], off
	global_load_dwordx4 v[176:179], v[138:139], off offset:64
	global_load_dwordx4 v[180:183], v[138:139], off offset:128
	global_load_dwordx4 v[184:187], v[138:139], off offset:192
	v_add_co_u32_e32 v138, vcc, 0x10000, v138
	s_nop 1
	v_addc_co_u32_e32 v139, vcc, 0, v139, vcc
	s_waitcnt vmcnt(12)
	v_pk_fma_f32 v[110:111], v[110:111], v[156:157], v[198:199]
	v_pk_fma_f32 v[112:113], v[112:113], v[158:159], v[200:201]
	v_pk_fma_f32 v[106:107], v[106:107], v[160:161], v[202:203]
	v_pk_fma_f32 v[108:109], v[108:109], v[162:163], v[204:205]
	v_pk_fma_f32 v[102:103], v[102:103], v[164:165], v[206:207]
	v_pk_fma_f32 v[104:105], v[104:105], v[166:167], v[208:209]
	v_pk_fma_f32 v[98:99], v[98:99], v[168:169], v[210:211]
	v_pk_fma_f32 v[100:101], v[100:101], v[170:171], v[212:213]
	global_store_dwordx4 v[140:141], v[110:113], off
	global_store_dwordx4 v[140:141], v[106:109], off offset:64
	global_store_dwordx4 v[140:141], v[102:105], off offset:128
	global_store_dwordx4 v[140:141], v[98:101], off offset:192
	v_add_co_u32_e32 v140, vcc, 0x10000, v140
	s_nop 1
	v_addc_co_u32_e32 v141, vcc, 0, v141, vcc
	global_load_dwordx4 v[198:201], v[138:139], off
	global_load_dwordx4 v[202:205], v[138:139], off offset:64
	global_load_dwordx4 v[206:209], v[138:139], off offset:128
	global_load_dwordx4 v[210:213], v[138:139], off offset:192
	v_add_co_u32_e32 v138, vcc, 0x10000, v138
	s_nop 1
	v_addc_co_u32_e32 v139, vcc, 0, v139, vcc
	s_waitcnt vmcnt(16)
; DI void phase_resid(char* smem, const Params& p, int layer, const bf16_t* A, int K, const bf16_t* W, int gate_idx, bool first) {
;     ...
;   auto ep = [&](int row, int col, float v0, float v1, float v2, float v3) {
;     const int b = row / TT, t = row - b * TT;
;     const float4 g = *(const float4*)(p.mod + (size_t)(layer * 5 + (t < CTXL ? 4 : b)) * 6144 + gate_idx * 1024 + col);
;     const float4 xo = *(const float4*)(xsrc_row(p, first, row) + col);
;     *(float4*)(xdst_row(p, row) + col) = make_float4(xo.x + g.x * v0, xo.y + g.y * v1, xo.z + g.z * v2, xo.w + g.w * v3);
	v_pk_fma_f32 v[94:95], v[94:95], v[156:157], v[214:215]
	v_pk_fma_f32 v[96:97], v[96:97], v[158:159], v[216:217]
	v_pk_fma_f32 v[90:91], v[90:91], v[160:161], v[218:219]
	v_pk_fma_f32 v[92:93], v[92:93], v[162:163], v[220:221]
	v_pk_fma_f32 v[86:87], v[86:87], v[164:165], v[222:223]
	v_pk_fma_f32 v[88:89], v[88:89], v[166:167], v[224:225]
	v_pk_fma_f32 v[82:83], v[82:83], v[168:169], v[142:143]
	v_pk_fma_f32 v[84:85], v[84:85], v[170:171], v[144:145]
	global_store_dwordx4 v[140:141], v[94:97], off
	global_store_dwordx4 v[140:141], v[90:93], off offset:64
	global_store_dwordx4 v[140:141], v[86:89], off offset:128
	global_store_dwordx4 v[140:141], v[82:85], off offset:192
	v_add_co_u32_e32 v140, vcc, 0x10000, v140
	s_nop 1
	v_addc_co_u32_e32 v141, vcc, 0, v141, vcc
	global_load_dwordx4 v[214:217], v[138:139], off
	global_load_dwordx4 v[218:221], v[138:139], off offset:64
	global_load_dwordx4 v[222:225], v[138:139], off offset:128
	global_load_dwordx4 v[142:145], v[138:139], off offset:192
	v_add_co_u32_e32 v138, vcc, 0x10000, v138
	s_nop 1
	v_addc_co_u32_e32 v139, vcc, 0, v139, vcc
	s_waitcnt vmcnt(16)
	v_pk_fma_f32 v[78:79], v[78:79], v[156:157], v[172:173]
	v_pk_fma_f32 v[80:81], v[80:81], v[158:159], v[174:175]
	v_pk_fma_f32 v[74:75], v[74:75], v[160:161], v[176:177]
	v_pk_fma_f32 v[76:77], v[76:77], v[162:163], v[178:179]
	v_pk_fma_f32 v[70:71], v[70:71], v[164:165], v[180:181]
	v_pk_fma_f32 v[72:73], v[72:73], v[166:167], v[182:183]
	v_pk_fma_f32 v[66:67], v[66:67], v[168:169], v[184:185]
	v_pk_fma_f32 v[68:69], v[68:69], v[170:171], v[186:187]
	global_store_dwordx4 v[140:141], v[78:81], off
	global_store_dwordx4 v[140:141], v[74:77], off offset:64
	global_store_dwordx4 v[140:141], v[70:73], off offset:128
	global_store_dwordx4 v[140:141], v[66:69], off offset:192
	v_add_co_u32_e32 v140, vcc, 0x10000, v140
	s_nop 1
	v_addc_co_u32_e32 v141, vcc, 0, v141, vcc
	global_load_dwordx4 v[172:175], v[138:139], off
	global_load_dwordx4 v[176:179], v[138:139], off offset:64
	global_load_dwordx4 v[180:183], v[138:139], off offset:128
	global_load_dwordx4 v[184:187], v[138:139], off offset:192
	v_add_co_u32_e32 v138, vcc, 0x10000, v138
	s_nop 1
	v_addc_co_u32_e32 v139, vcc, 0, v139, vcc
	s_waitcnt vmcnt(16)
	v_pk_fma_f32 v[62:63], v[62:63], v[156:157], v[198:199]
	v_pk_fma_f32 v[64:65], v[64:65], v[158:159], v[200:201]
	v_pk_fma_f32 v[58:59], v[58:59], v[160:161], v[202:203]
	v_pk_fma_f32 v[60:61], v[60:61], v[162:163], v[204:205]
	v_pk_fma_f32 v[54:55], v[54:55], v[164:165], v[206:207]
	v_pk_fma_f32 v[56:57], v[56:57], v[166:167], v[208:209]
	v_pk_fma_f32 v[50:51], v[50:51], v[168:169], v[210:211]
	v_pk_fma_f32 v[52:53], v[52:53], v[170:171], v[212:213]
	global_store_dwordx4 v[140:141], v[62:65], off
	global_store_dwordx4 v[140:141], v[58:61], off offset:64
	global_store_dwordx4 v[140:141], v[54:57], off offset:128
	global_store_dwordx4 v[140:141], v[50:53], off offset:192
	v_add_co_u32_e32 v140, vcc, 0x10000, v140
	s_nop 1
	v_addc_co_u32_e32 v141, vcc, 0, v141, vcc
	global_load_dwordx4 v[198:201], v[138:139], off
	global_load_dwordx4 v[202:205], v[138:139], off offset:64
	global_load_dwordx4 v[206:209], v[138:139], off offset:128
	global_load_dwordx4 v[210:213], v[138:139], off offset:192
	s_waitcnt vmcnt(16)
	v_pk_fma_f32 v[46:47], v[46:47], v[156:157], v[214:215]
	v_pk_fma_f32 v[48:49], v[48:49], v[158:159], v[216:217]
	v_pk_fma_f32 v[42:43], v[42:43], v[160:161], v[218:219]
	v_pk_fma_f32 v[44:45], v[44:45], v[162:163], v[220:221]
	v_pk_fma_f32 v[38:39], v[38:39], v[164:165], v[222:223]
	v_pk_fma_f32 v[40:41], v[40:41], v[166:167], v[224:225]
	v_pk_fma_f32 v[34:35], v[34:35], v[168:169], v[142:143]
	v_pk_fma_f32 v[36:37], v[36:37], v[170:171], v[144:145]
	global_store_dwordx4 v[140:141], v[46:49], off
	global_store_dwordx4 v[140:141], v[42:45], off offset:64
	global_store_dwordx4 v[140:141], v[38:41], off offset:128
	global_store_dwordx4 v[140:141], v[34:37], off offset:192
	v_add_co_u32_e32 v140, vcc, 0x10000, v140
	s_nop 1
	v_addc_co_u32_e32 v141, vcc, 0, v141, vcc
	s_waitcnt vmcnt(12)
	v_pk_fma_f32 v[30:31], v[30:31], v[156:157], v[172:173]
	v_pk_fma_f32 v[32:33], v[32:33], v[158:159], v[174:175]
	v_pk_fma_f32 v[26:27], v[26:27], v[160:161], v[176:177]
	v_pk_fma_f32 v[28:29], v[28:29], v[162:163], v[178:179]
	v_pk_fma_f32 v[22:23], v[22:23], v[164:165], v[180:181]
	v_pk_fma_f32 v[24:25], v[24:25], v[166:167], v[182:183]
	v_pk_fma_f32 v[18:19], v[18:19], v[168:169], v[184:185]
	v_pk_fma_f32 v[20:21], v[20:21], v[170:171], v[186:187]
	global_store_dwordx4 v[140:141], v[30:33], off
	global_store_dwordx4 v[140:141], v[26:29], off offset:64
	global_store_dwordx4 v[140:141], v[22:25], off offset:128
	global_store_dwordx4 v[140:141], v[18:21], off offset:192
	v_add_co_u32_e32 v140, vcc, 0x10000, v140
	s_nop 1
	v_addc_co_u32_e32 v141, vcc, 0, v141, vcc
	s_waitcnt vmcnt(8)
	v_pk_fma_f32 v[14:15], v[14:15], v[156:157], v[198:199]
	v_pk_fma_f32 v[16:17], v[16:17], v[158:159], v[200:201]
	v_pk_fma_f32 v[10:11], v[10:11], v[160:161], v[202:203]
	v_pk_fma_f32 v[12:13], v[12:13], v[162:163], v[204:205]
	v_pk_fma_f32 v[6:7], v[6:7], v[164:165], v[206:207]
	v_pk_fma_f32 v[8:9], v[8:9], v[166:167], v[208:209]
	v_pk_fma_f32 v[2:3], v[2:3], v[168:169], v[210:211]
	v_pk_fma_f32 v[4:5], v[4:5], v[170:171], v[212:213]
	global_store_dwordx4 v[140:141], v[14:17], off
	global_store_dwordx4 v[140:141], v[10:13], off offset:64
	global_store_dwordx4 v[140:141], v[6:9], off offset:128
	global_store_dwordx4 v[140:141], v[2:5], off offset:192
	s_branch .LBB0_41

; DI int tid_() { int t = threadIdx.x; asm volatile("" : "+v"(t)); return t; }
;     ...
;   const int tid = tid_(), w = tid >> 6, l = tid & 63, r16 = l & 15, q4 = l >> 4;
;   const int wm = w >> 2, wn = w & 3;
;   f32x4 acc[MT][4];
; #pragma unroll
;   for (int a = 0; a < MT; ++a)
; #pragma unroll
;     for (int b = 0; b < 4; ++b) { acc[a][b][0] = 0.f; acc[a][b][1] = 0.f; acc[a][b][2] = 0.f; acc[a][b][3] = 0.f; }
;   const int srow = tid >> 3, slog = (tid & 7) ^ ((tid >> 4) & 7);
;   const bf16_t* Ag = A + (size_t)(m0 + srow) * lda + slog * 8;
;   const bf16_t* Bg0 = B + (size_t)min(n0 + srow, N - 1) * ldb + slog * 8;
;   const bf16_t* Bg1 = B + (size_t)min(n0 + srow + 64, N - 1) * ldb + slog * 8;
;   const bf16_t* Bg2 = B + (size_t)min(n0 + srow + 128, N - 1) * ldb + slog * 8;
;   const bf16_t* Bg3 = B + (size_t)min(n0 + srow + 192, N - 1) * ldb + slog * 8;
;   char* wbase = smem + w * 1024;
;     ...
;   const int nk = K >> 6;
;   __syncthreads();
;   STAGE_TILE(0, 0)
;   asm volatile("s_waitcnt vmcnt(0)" ::: "memory");
;   __syncthreads();
.LBB0_106:
	v_mov_b32_e32 v16, v0
	s_lshl_b32 s44, s44, 8
	v_readlane_b32 s52, v253, 40
	v_ashrrev_i32_e32 v4, 3, v16
	v_lshrrev_b32_e32 v17, 4, v16
	v_add_u32_e32 v2, s44, v4
	v_xor_b32_e32 v5, v17, v16
	v_ashrrev_i32_e32 v3, 31, v2
	v_ashrrev_i32_e32 v14, 6, v16
	v_lshlrev_b64 v[2:3], 11, v[2:3]
	v_readlane_b32 s53, v253, 41
	v_lshlrev_b32_e32 v5, 4, v5
	s_lshl_b32 s43, s45, 8
	v_lshl_add_u64 v[2:3], s[52:53], 0, v[2:3]
	v_and_b32_e32 v190, 0x70, v5
	v_lshl_add_u32 v145, v14, 10, 0
	v_lshl_add_u64 v[130:131], v[2:3], 0, v[190:191]
	v_add_u32_e32 v2, s43, v4
	v_readfirstlane_b32 s22, v145
	v_add_u32_e32 v3, 0x2000, v145
	v_min_i32_e32 v4, 0x3ff, v2
	v_min_i32_e32 v8, 0x3bf, v2
	s_mov_b64 s[46:47], 0x20000
	s_mov_b32 m0, s22
	v_readfirstlane_b32 s22, v3
	v_add_u32_e32 v3, 0x4000, v145
	v_and_b32_e32 v143, 3, v14
	v_ashrrev_i32_e32 v5, 31, v4
	v_ashrrev_i32_e32 v9, 31, v8
	v_min_i32_e32 v10, 0x37f, v2
	s_mov_b64 s[48:49], 0x40000
	s_barrier
	global_load_lds_dwordx4 v[130:131], off
	v_lshl_add_u64 v[14:15], v[130:131], 0, s[46:47]
	s_mov_b32 m0, s22
	v_readfirstlane_b32 s22, v3
	v_add_u32_e32 v3, 0x6000, v145
	v_lshlrev_b64 v[4:5], 11, v[4:5]
	v_lshlrev_b64 v[8:9], 11, v[8:9]
	v_ashrrev_i32_e32 v11, 31, v10
	v_min_i32_e32 v12, 0x33f, v2
	s_mov_b64 s[50:51], 0x60000
	global_load_lds_dwordx4 v[14:15], off
	v_lshl_add_u64 v[14:15], v[130:131], 0, s[48:49]
	s_mov_b32 m0, s22
	v_readfirstlane_b32 s22, v3
	v_add_u32_e32 v3, 0x8000, v145
	v_lshl_add_u64 v[6:7], s[2:3], 0, v[4:5]
	v_lshl_add_u64 v[8:9], s[2:3], 0, v[8:9]
	v_lshlrev_b64 v[10:11], 11, v[10:11]
	v_ashrrev_i32_e32 v13, 31, v12
	global_load_lds_dwordx4 v[14:15], off
	v_lshl_add_u64 v[14:15], v[130:131], 0, s[50:51]
	s_mov_b32 m0, s22
	v_readfirstlane_b32 s22, v3
	v_add_u32_e32 v3, 0xa000, v145
	v_lshl_add_u64 v[6:7], v[6:7], 0, v[190:191]
	v_lshl_add_u64 v[8:9], v[8:9], 0, v[190:191]
	v_lshl_add_u64 v[10:11], s[2:3], 0, v[10:11]
	v_lshlrev_b64 v[12:13], 11, v[12:13]
	global_load_lds_dwordx4 v[14:15], off
	s_mov_b32 m0, s22
	v_readfirstlane_b32 s22, v3
	v_add_u32_e32 v3, 0xc000, v145
	v_lshl_add_u64 v[8:9], v[8:9], 0, s[46:47]
	v_lshl_add_u64 v[10:11], v[10:11], 0, v[190:191]
	v_lshl_add_u64 v[12:13], s[2:3], 0, v[12:13]
	global_load_lds_dwordx4 v[6:7], off
	s_mov_b32 m0, s22
	v_readfirstlane_b32 s22, v3
	v_add_u32_e32 v3, 0xe000, v145
	v_lshl_add_u64 v[10:11], v[10:11], 0, s[48:49]
	v_lshl_add_u64 v[12:13], v[12:13], 0, v[190:191]
	global_load_lds_dwordx4 v[8:9], off
	s_mov_b32 m0, s22
	v_readfirstlane_b32 s22, v3
	v_lshl_add_u64 v[12:13], v[12:13], 0, s[50:51]
	global_load_lds_dwordx4 v[10:11], off
	s_mov_b32 m0, s22
	v_and_b32_e32 v142, 15, v16
	global_load_lds_dwordx4 v[12:13], off
	v_ashrrev_i32_e32 v140, 8, v16
	v_bfe_u32 v141, v16, 4, 2
	v_bfe_u32 v3, v16, 1, 3
	v_lshlrev_b32_e32 v6, 7, v142
	v_lshl_or_b32 v148, v140, 14, v6
	v_lshl_or_b32 v147, v143, 13, v6
	v_bitop3_b32 v6, v17, v3, 3 bitop3:0x6c
	v_bitop3_b32 v3, v141, v3, 4 bitop3:0x36
	v_lshlrev_b32_e32 v144, 4, v3
	v_ashrrev_i32_e32 v3, 31, v2
	s_mov_b64 s[22:23], 0x33f
	v_cmp_gt_i64_e32 vcc, s[22:23], v[2:3]
	v_lshlrev_b32_e32 v146, 4, v6
	v_bitop3_b32 v8, v17, 7, v16 bitop3:0x48
	v_cndmask_b32_e32 v7, 0, v3, vcc
	v_cndmask_b32_e32 v6, v227, v2, vcc
	v_lshlrev_b64 v[6:7], 11, v[6:7]
	v_lshlrev_b32_e32 v8, 4, v8
	s_mov_b64 s[22:23], 0x37f
	v_or_b32_e32 v6, v6, v8
	v_cmp_gt_i64_e32 vcc, s[22:23], v[2:3]
	s_mov_b64 s[22:23], 0x3bf
	v_lshl_add_u64 v[132:133], s[12:13], 0, v[6:7]
	v_cndmask_b32_e32 v7, 0, v3, vcc
	v_cndmask_b32_e32 v6, v197, v2, vcc
	v_cmp_gt_i64_e32 vcc, s[22:23], v[2:3]
	s_waitcnt vmcnt(0)
	v_lshlrev_b64 v[6:7], 11, v[6:7]
	v_or_b32_e32 v6, v6, v8
	v_cndmask_b32_e32 v3, 0, v3, vcc
	v_cndmask_b32_e32 v2, v195, v2, vcc
	v_lshlrev_b64 v[2:3], 11, v[2:3]
	v_or_b32_e32 v2, v2, v8
	v_lshl_add_u64 v[136:137], s[16:17], 0, v[2:3]
	v_or_b32_e32 v4, v4, v8
	v_mov_b32_e32 v2, 0
	s_mov_b32 s45, 0
	v_lshl_add_u64 v[134:135], s[14:15], 0, v[6:7]
	v_lshl_add_u64 v[138:139], s[20:21], 0, v[4:5]
	s_mov_b64 s[22:23], 0
	v_mov_b32_e32 v3, v2
	v_mov_b32_e32 v4, v2
	v_mov_b32_e32 v5, v2
	v_mov_b32_e32 v6, v2
	v_mov_b32_e32 v7, v2
	v_mov_b32_e32 v8, v2
	v_mov_b32_e32 v9, v2
	v_mov_b32_e32 v10, v2
	v_mov_b32_e32 v11, v2
	v_mov_b32_e32 v12, v2
	v_mov_b32_e32 v13, v2
	v_mov_b32_e32 v14, v2
	v_mov_b32_e32 v15, v2
	v_mov_b32_e32 v16, v2
	v_mov_b32_e32 v17, v2
	v_mov_b32_e32 v18, v2
	v_mov_b32_e32 v19, v2
	v_mov_b32_e32 v20, v2
	v_mov_b32_e32 v21, v2
	v_mov_b32_e32 v22, v2
	v_mov_b32_e32 v23, v2
	v_mov_b32_e32 v24, v2
	v_mov_b32_e32 v25, v2
	v_mov_b32_e32 v26, v2
	v_mov_b32_e32 v27, v2
	v_mov_b32_e32 v28, v2
	v_mov_b32_e32 v29, v2
	v_mov_b32_e32 v30, v2
	v_mov_b32_e32 v31, v2
	v_mov_b32_e32 v32, v2
	v_mov_b32_e32 v33, v2
	v_mov_b32_e32 v34, v2
	v_mov_b32_e32 v35, v2
	v_mov_b32_e32 v36, v2
	v_mov_b32_e32 v37, v2
	v_mov_b32_e32 v38, v2
	v_mov_b32_e32 v39, v2
	v_mov_b32_e32 v40, v2
	v_mov_b32_e32 v41, v2
	v_mov_b32_e32 v42, v2
	v_mov_b32_e32 v43, v2
	v_mov_b32_e32 v44, v2
	v_mov_b32_e32 v45, v2
	v_mov_b32_e32 v46, v2
	v_mov_b32_e32 v47, v2
	v_mov_b32_e32 v48, v2
	v_mov_b32_e32 v49, v2
	v_mov_b32_e32 v50, v2
	v_mov_b32_e32 v51, v2
	v_mov_b32_e32 v52, v2
	v_mov_b32_e32 v53, v2
	v_mov_b32_e32 v54, v2
	v_mov_b32_e32 v55, v2
	v_mov_b32_e32 v56, v2
	v_mov_b32_e32 v57, v2
	v_mov_b32_e32 v58, v2
	v_mov_b32_e32 v59, v2
	v_mov_b32_e32 v60, v2
	v_mov_b32_e32 v61, v2
	v_mov_b32_e32 v62, v2
	v_mov_b32_e32 v63, v2
	v_mov_b32_e32 v64, v2
	v_mov_b32_e32 v65, v2
	v_mov_b32_e32 v66, v2
	v_mov_b32_e32 v67, v2
	v_mov_b32_e32 v68, v2
	v_mov_b32_e32 v69, v2
	v_mov_b32_e32 v70, v2
	v_mov_b32_e32 v71, v2
	v_mov_b32_e32 v72, v2
	v_mov_b32_e32 v73, v2
	v_mov_b32_e32 v74, v2
	v_mov_b32_e32 v75, v2
	v_mov_b32_e32 v76, v2
	v_mov_b32_e32 v77, v2
	v_mov_b32_e32 v78, v2
	v_mov_b32_e32 v79, v2
	v_mov_b32_e32 v80, v2
	v_mov_b32_e32 v81, v2
	s_waitcnt vmcnt(0)
;     ...
;   f32x4 acc[MT][4];
; #pragma unroll
;   for (int a = 0; a < MT; ++a)
; #pragma unroll
;     for (int b = 0; b < 4; ++b) { acc[a][b][0] = 0.f; acc[a][b][1] = 0.f; acc[a][b][2] = 0.f; acc[a][b][3] = 0.f; }
	v_mov_b32_e32 v82, v2
	v_mov_b32_e32 v83, v2
	v_mov_b32_e32 v84, v2
	v_mov_b32_e32 v85, v2
	v_mov_b32_e32 v86, v2
	v_mov_b32_e32 v87, v2
	v_mov_b32_e32 v88, v2
	v_mov_b32_e32 v89, v2
	v_mov_b32_e32 v90, v2
	v_mov_b32_e32 v91, v2
	v_mov_b32_e32 v92, v2
	v_mov_b32_e32 v93, v2
	v_mov_b32_e32 v94, v2
	v_mov_b32_e32 v95, v2
	v_mov_b32_e32 v96, v2
	v_mov_b32_e32 v97, v2
	v_mov_b32_e32 v98, v2
	v_mov_b32_e32 v99, v2
	v_mov_b32_e32 v100, v2
	v_mov_b32_e32 v101, v2
	v_mov_b32_e32 v102, v2
	v_mov_b32_e32 v103, v2
	v_mov_b32_e32 v104, v2
	v_mov_b32_e32 v105, v2
	v_mov_b32_e32 v106, v2
	v_mov_b32_e32 v107, v2
	v_mov_b32_e32 v108, v2
	v_mov_b32_e32 v109, v2
	v_mov_b32_e32 v110, v2
	v_mov_b32_e32 v111, v2
	v_mov_b32_e32 v112, v2
	v_mov_b32_e32 v113, v2
	v_mov_b32_e32 v114, v2
	v_mov_b32_e32 v115, v2
	v_mov_b32_e32 v116, v2
	v_mov_b32_e32 v117, v2
	v_mov_b32_e32 v118, v2
	v_mov_b32_e32 v119, v2
	v_mov_b32_e32 v120, v2
	v_mov_b32_e32 v121, v2
	v_mov_b32_e32 v122, v2
	v_mov_b32_e32 v123, v2
	v_mov_b32_e32 v124, v2
	v_mov_b32_e32 v125, v2
	v_mov_b32_e32 v126, v2
	v_mov_b32_e32 v127, v2
	v_mov_b32_e32 v128, v2
	v_mov_b32_e32 v129, v2
	v_readlane_b32 s54, v253, 42
	v_readlane_b32 s55, v253, 43
	v_readlane_b32 s56, v253, 44
	v_readlane_b32 s57, v253, 45
	v_readlane_b32 s58, v253, 46
	v_readlane_b32 s59, v253, 47
	v_readlane_b32 s60, v253, 48
	v_readlane_b32 s61, v253, 49
	v_readlane_b32 s62, v253, 50
	v_readlane_b32 s63, v253, 51
	v_readlane_b32 s64, v253, 52
	v_readlane_b32 s65, v253, 53
	v_readlane_b32 s66, v253, 54
	v_readlane_b32 s67, v253, 55
	s_waitcnt vmcnt(0) lgkmcnt(0)
	s_barrier
	v_readfirstlane_b32 s100, v138
	v_readfirstlane_b32 s101, v139
	s_nop 0
	s_sub_u32 s100, s100, 0x80
	s_subb_u32 s101, s101, 0
	v_add_u32_e32 v176, s24, v130
	v_subrev_u32_e32 v176, s100, v176
	v_add_u32_e32 v177, s84, v130
	v_subrev_u32_e32 v177, s100, v177
	v_add_u32_e32 v178, s28, v130
	v_subrev_u32_e32 v178, s100, v178
	v_add_u32_e32 v179, s18, v130
	v_subrev_u32_e32 v179, s100, v179
	v_subrev_u32_e32 v180, s100, v138
	v_subrev_u32_e32 v181, s100, v136
	v_subrev_u32_e32 v182, s100, v134
	v_subrev_u32_e32 v183, s100, v132
; #define MFMA16(a, b, c) __builtin_amdgcn_mfma_f32_16x16x32_bf16((a), (b), (c), 0, 0, 0)
;     ...
;   for (int kt = 0; kt < nk; ++kt) {
;     const int buf = kt & 1;
;     const char* cA = smem + buf * STAGE + (wm * 32 * MI + r16) * 128;
;     const char* cB = smem + buf * STAGE + 32768 + (wn * 64 + r16) * 128;
; #pragma unroll
;     for (int k2 = 0; k2 < 2; ++k2) {
;       if (k2 == 1 && kt + 1 < nk) STAGE_TILE(buf ^ 1, (kt + 1) * 64)
;       const int po = ((4 * k2 + q4) ^ swz) * 16;
;       bf16x8 bf[4];
; #pragma unroll
;       for (int nt = 0; nt < 4; ++nt) bf[nt] = *(const bf16x8*)(cB + nt * 16 * 128 + po);
;       bf16x8 afc = *(const bf16x8*)(cA + po);
; #pragma unroll
;       for (int a = 0; a < MT; ++a) {
;         bf16x8 afn = afc;
;         if (a + 1 < MT) afn = *(const bf16x8*)(cA + (a + 1) * 16 * 128 + po);
;         __builtin_amdgcn_sched_barrier(0);
; #pragma unroll
;         for (int nt = 0; nt < 4; ++nt) acc[a][nt] = MFMA16(bf[nt], afc, acc[a][nt]);
;         __builtin_amdgcn_sched_barrier(0);
;         afc = afn;
;       }
;     }
;     asm volatile("s_waitcnt vmcnt(0)" ::: "memory");
;     __syncthreads();
;   }
.LBB0_107:
	s_and_b32 s46, s45, 0x10000
	s_add_i32 s47, s46, 0
	v_add_u32_e32 v174, s47, v147
	v_add_u32_e32 v162, v174, v146
	v_add_u32_e32 v149, s47, v148
	ds_read_b128 v[150:153], v162 offset:32768
	ds_read_b128 v[154:157], v162 offset:34816
	ds_read_b128 v[158:161], v162 offset:36864
	ds_read_b128 v[162:165], v162 offset:38912
	v_add_u32_e32 v175, v149, v146
	ds_read_b128 v[166:169], v175
	ds_read_b128 v[170:173], v175 offset:2048
	s_waitcnt lgkmcnt(1)
	v_mfma_f32_16x16x32_bf16 v[126:129], v[150:153], v[166:169], v[126:129]
	v_mfma_f32_16x16x32_bf16 v[122:125], v[154:157], v[166:169], v[122:125]
	v_mfma_f32_16x16x32_bf16 v[118:121], v[158:161], v[166:169], v[118:121]
	v_mfma_f32_16x16x32_bf16 v[114:117], v[162:165], v[166:169], v[114:117]
	ds_read_b128 v[166:169], v175 offset:4096
	s_waitcnt lgkmcnt(1)
	v_mfma_f32_16x16x32_bf16 v[110:113], v[150:153], v[170:173], v[110:113]
	v_mfma_f32_16x16x32_bf16 v[106:109], v[154:157], v[170:173], v[106:109]
	v_mfma_f32_16x16x32_bf16 v[102:105], v[158:161], v[170:173], v[102:105]
	v_mfma_f32_16x16x32_bf16 v[98:101], v[162:165], v[170:173], v[98:101]
	ds_read_b128 v[170:173], v175 offset:6144
	s_waitcnt lgkmcnt(1)
	v_mfma_f32_16x16x32_bf16 v[94:97], v[150:153], v[166:169], v[94:97]
	v_mfma_f32_16x16x32_bf16 v[90:93], v[154:157], v[166:169], v[90:93]
	v_mfma_f32_16x16x32_bf16 v[86:89], v[158:161], v[166:169], v[86:89]
	v_mfma_f32_16x16x32_bf16 v[82:85], v[162:165], v[166:169], v[82:85]
	ds_read_b128 v[166:169], v175 offset:8192
	s_waitcnt lgkmcnt(1)
	v_mfma_f32_16x16x32_bf16 v[78:81], v[150:153], v[170:173], v[78:81]
	v_mfma_f32_16x16x32_bf16 v[74:77], v[154:157], v[170:173], v[74:77]
	v_mfma_f32_16x16x32_bf16 v[70:73], v[158:161], v[170:173], v[70:73]
	v_mfma_f32_16x16x32_bf16 v[66:69], v[162:165], v[170:173], v[66:69]
	ds_read_b128 v[170:173], v175 offset:10240
	s_waitcnt lgkmcnt(1)
	v_mfma_f32_16x16x32_bf16 v[62:65], v[150:153], v[166:169], v[62:65]
	v_mfma_f32_16x16x32_bf16 v[58:61], v[154:157], v[166:169], v[58:61]
	v_mfma_f32_16x16x32_bf16 v[54:57], v[158:161], v[166:169], v[54:57]
	v_mfma_f32_16x16x32_bf16 v[50:53], v[162:165], v[166:169], v[50:53]
	ds_read_b128 v[166:169], v175 offset:12288
	s_waitcnt lgkmcnt(1)
	v_mfma_f32_16x16x32_bf16 v[46:49], v[150:153], v[170:173], v[46:49]
	v_mfma_f32_16x16x32_bf16 v[42:45], v[154:157], v[170:173], v[42:45]
	v_mfma_f32_16x16x32_bf16 v[38:41], v[158:161], v[170:173], v[38:41]
	v_mfma_f32_16x16x32_bf16 v[34:37], v[162:165], v[170:173], v[34:37]
	ds_read_b128 v[170:173], v175 offset:14336
	s_waitcnt lgkmcnt(1)
	v_mfma_f32_16x16x32_bf16 v[30:33], v[150:153], v[166:169], v[30:33]
	v_mfma_f32_16x16x32_bf16 v[26:29], v[154:157], v[166:169], v[26:29]
	v_mfma_f32_16x16x32_bf16 v[22:25], v[158:161], v[166:169], v[22:25]
	v_mfma_f32_16x16x32_bf16 v[18:21], v[162:165], v[166:169], v[18:21]
	s_waitcnt lgkmcnt(0)
	v_mfma_f32_16x16x32_bf16 v[14:17], v[150:153], v[170:173], v[14:17]
	v_mfma_f32_16x16x32_bf16 v[10:13], v[154:157], v[170:173], v[10:13]
	v_mfma_f32_16x16x32_bf16 v[6:9], v[158:161], v[170:173], v[6:9]
	v_mfma_f32_16x16x32_bf16 v[2:5], v[162:165], v[170:173], v[2:5]
	s_xor_b32 s46, s46, 0x10000
	v_readfirstlane_b32 s47, v145
	s_nop 0
	s_add_u32 s47, s47, s46
	s_add_u32 m0, s47, 0x0
	s_nop 0
	global_load_lds_dwordx4 v176, s[100:101]
	s_add_u32 m0, s47, 0x2000
	s_nop 0
	global_load_lds_dwordx4 v177, s[100:101]
	s_add_u32 m0, s47, 0x4000
	s_nop 0
	global_load_lds_dwordx4 v178, s[100:101]
	s_add_u32 m0, s47, 0x6000
	s_nop 0
	global_load_lds_dwordx4 v179, s[100:101]
	s_add_u32 m0, s47, 0x8000
	s_nop 0
	global_load_lds_dwordx4 v180, s[100:101]
	s_add_u32 m0, s47, 0xa000
	s_nop 0
	global_load_lds_dwordx4 v181, s[100:101]
	s_add_u32 m0, s47, 0xc000
	s_nop 0
	global_load_lds_dwordx4 v182, s[100:101]
	s_add_u32 m0, s47, 0xe000
	s_nop 0
	global_load_lds_dwordx4 v183, s[100:101]
	v_add_u32_e32 v162, v174, v144
	ds_read_b128 v[150:153], v162 offset:32768
	ds_read_b128 v[154:157], v162 offset:34816
	ds_read_b128 v[158:161], v162 offset:36864
	ds_read_b128 v[162:165], v162 offset:38912
	v_add_u32_e32 v149, v149, v144
	ds_read_b128 v[166:169], v149
	ds_read_b128 v[170:173], v149 offset:2048
	s_waitcnt lgkmcnt(0)
	v_mfma_f32_16x16x32_bf16 v[126:129], v[150:153], v[166:169], v[126:129]
	v_mfma_f32_16x16x32_bf16 v[122:125], v[154:157], v[166:169], v[122:125]
	v_mfma_f32_16x16x32_bf16 v[118:121], v[158:161], v[166:169], v[118:121]
	v_mfma_f32_16x16x32_bf16 v[114:117], v[162:165], v[166:169], v[114:117]
	ds_read_b128 v[166:169], v149 offset:4096
	v_mfma_f32_16x16x32_bf16 v[110:113], v[150:153], v[170:173], v[110:113]
	v_mfma_f32_16x16x32_bf16 v[106:109], v[154:157], v[170:173], v[106:109]
	v_mfma_f32_16x16x32_bf16 v[102:105], v[158:161], v[170:173], v[102:105]
	v_mfma_f32_16x16x32_bf16 v[98:101], v[162:165], v[170:173], v[98:101]
	ds_read_b128 v[170:173], v149 offset:6144
	s_waitcnt lgkmcnt(0)
	v_mfma_f32_16x16x32_bf16 v[94:97], v[150:153], v[166:169], v[94:97]
	v_mfma_f32_16x16x32_bf16 v[90:93], v[154:157], v[166:169], v[90:93]
	v_mfma_f32_16x16x32_bf16 v[86:89], v[158:161], v[166:169], v[86:89]
	v_mfma_f32_16x16x32_bf16 v[82:85], v[162:165], v[166:169], v[82:85]
	ds_read_b128 v[166:169], v149 offset:8192
	v_mfma_f32_16x16x32_bf16 v[78:81], v[150:153], v[170:173], v[78:81]
	v_mfma_f32_16x16x32_bf16 v[74:77], v[154:157], v[170:173], v[74:77]
	v_mfma_f32_16x16x32_bf16 v[70:73], v[158:161], v[170:173], v[70:73]
	v_mfma_f32_16x16x32_bf16 v[66:69], v[162:165], v[170:173], v[66:69]
	ds_read_b128 v[170:173], v149 offset:10240
	s_waitcnt lgkmcnt(0)
	v_mfma_f32_16x16x32_bf16 v[62:65], v[150:153], v[166:169], v[62:65]
	v_mfma_f32_16x16x32_bf16 v[58:61], v[154:157], v[166:169], v[58:61]
	v_mfma_f32_16x16x32_bf16 v[54:57], v[158:161], v[166:169], v[54:57]
	v_mfma_f32_16x16x32_bf16 v[50:53], v[162:165], v[166:169], v[50:53]
	ds_read_b128 v[166:169], v149 offset:12288
	v_mfma_f32_16x16x32_bf16 v[46:49], v[150:153], v[170:173], v[46:49]
	v_mfma_f32_16x16x32_bf16 v[42:45], v[154:157], v[170:173], v[42:45]
	v_mfma_f32_16x16x32_bf16 v[38:41], v[158:161], v[170:173], v[38:41]
	v_mfma_f32_16x16x32_bf16 v[34:37], v[162:165], v[170:173], v[34:37]
	ds_read_b128 v[170:173], v149 offset:14336
	s_waitcnt lgkmcnt(0)
	v_mfma_f32_16x16x32_bf16 v[30:33], v[150:153], v[166:169], v[30:33]
	v_mfma_f32_16x16x32_bf16 v[26:29], v[154:157], v[166:169], v[26:29]
	v_mfma_f32_16x16x32_bf16 v[22:25], v[158:161], v[166:169], v[22:25]
	v_mfma_f32_16x16x32_bf16 v[18:21], v[162:165], v[166:169], v[18:21]
	v_mfma_f32_16x16x32_bf16 v[14:17], v[150:153], v[170:173], v[14:17]
	v_mfma_f32_16x16x32_bf16 v[10:13], v[154:157], v[170:173], v[10:13]
	v_mfma_f32_16x16x32_bf16 v[6:9], v[158:161], v[170:173], v[6:9]
	v_mfma_f32_16x16x32_bf16 v[2:5], v[162:165], v[170:173], v[2:5]
	s_waitcnt vmcnt(0)
	s_add_u32 s100, s100, 0x80
	s_addc_u32 s101, s101, 0
	s_add_u32 s22, s22, 0x80
	s_addc_u32 s23, s23, 0
	s_add_i32 s45, s45, 0x10000
	s_cmpk_eq_i32 s22, 0x780
	s_waitcnt vmcnt(0)
	s_barrier
	s_cbranch_scc0 .LBB0_107
	s_branch .LBB0_99
